# narrow lr-column tile: three-stage LDS-DMA ring (20 KiB stages) so each DMA group has ~2.75 K-steps to land
# baseline (speedup 1.0000x reference)
.LBB0_233:
	v_cmp_ne_u32_e32 vcc, 0, v4
	v_mov_b32_e32 v5, s15
	ds_write_b32 v5, v4
	s_cbranch_vccnz .LBB0_237
	v_cmp_ne_u32_e32 vcc, -1, v255
	s_cbranch_vccz .Lqp_nopref
	s_waitcnt vmcnt(8)
	v_mov_b32_e32 v2, v255
	v_mov_b32_e32 v255, -1
	s_branch .LBB0_237

.Lg1_narrow:
	s_add_u32 m0, s4, 0x0
	s_nop 0
	global_load_lds_dwordx4 v56, s[0:1]
	s_add_u32 m0, s4, 0x1000
	s_nop 0
	global_load_lds_dwordx4 v57, s[0:1]
	s_add_u32 m0, s4, 0x2000
	s_nop 0
	global_load_lds_dwordx4 v58, s[0:1]
	s_add_u32 m0, s4, 0x3000
	s_nop 0
	global_load_lds_dwordx4 v59, s[0:1]
	s_add_u32 m0, s4, 0x4000
	s_nop 0
	global_load_lds_dwordx4 v56, s[2:3]
	s_add_u32 s0, s0, 0x80
	s_addc_u32 s1, s1, 0
	s_add_u32 s2, s2, 0x80
	s_addc_u32 s3, s3, 0
	s_add_u32 m0, s4, 0x5000
	s_nop 0
	global_load_lds_dwordx4 v56, s[0:1]
	s_add_u32 m0, s4, 0x6000
	s_nop 0
	global_load_lds_dwordx4 v57, s[0:1]
	s_add_u32 m0, s4, 0x7000
	s_nop 0
	global_load_lds_dwordx4 v58, s[0:1]
	s_add_u32 m0, s4, 0x8000
	s_nop 0
	global_load_lds_dwordx4 v59, s[0:1]
	s_add_u32 m0, s4, 0x9000
	s_nop 0
	global_load_lds_dwordx4 v56, s[2:3]
	s_add_u32 s0, s0, 0x80
	s_addc_u32 s1, s1, 0
	s_add_u32 s2, s2, 0x80
	s_addc_u32 s3, s3, 0
	s_add_u32 m0, s4, 0xa000
	s_nop 0
	global_load_lds_dwordx4 v56, s[0:1]
	s_add_u32 m0, s4, 0xb000
	s_nop 0
	global_load_lds_dwordx4 v57, s[0:1]
	s_add_u32 m0, s4, 0xc000
	s_nop 0
	global_load_lds_dwordx4 v58, s[0:1]
	s_add_u32 m0, s4, 0xd000
	s_nop 0
	global_load_lds_dwordx4 v59, s[0:1]
	s_add_u32 m0, s4, 0xe000
	s_nop 0
	global_load_lds_dwordx4 v56, s[2:3]
	s_add_u32 s0, s0, 0x80
	s_addc_u32 s1, s1, 0
	s_add_u32 s2, s2, 0x80
	s_addc_u32 s3, s3, 0
	s_waitcnt vmcnt(10)
	s_barrier
	ds_read_b128 v[140:143], v66 offset:0
	ds_read_b128 v[144:147], v66 offset:2048
	ds_read_b128 v[156:159], v64 offset:0
	ds_read_b128 v[160:163], v64 offset:2048
	ds_read_b128 v[164:167], v64 offset:4096
	ds_read_b128 v[168:171], v64 offset:6144
	ds_read_b128 v[172:175], v67 offset:0
	ds_read_b128 v[176:179], v67 offset:2048
	ds_read_b128 v[188:191], v65 offset:0
	ds_read_b128 v[192:195], v65 offset:2048
	ds_read_b128 v[196:199], v65 offset:4096
	ds_read_b128 v[200:203], v65 offset:6144
	s_waitcnt lgkmcnt(0)
	s_barrier
	v_mfma_f32_16x16x32_bf16 v[60:63], v[140:143], v[156:159], v[60:63]
	v_mfma_f32_16x16x32_bf16 v[68:71], v[140:143], v[160:163], v[68:71]
	s_add_u32 m0, s4, 0x0
	s_nop 0
	global_load_lds_dwordx4 v56, s[0:1]
	v_mfma_f32_16x16x32_bf16 v[52:55], v[140:143], v[164:167], v[52:55]
	v_mfma_f32_16x16x32_bf16 v[40:43], v[140:143], v[168:171], v[40:43]
	s_add_u32 m0, s4, 0x1000
	s_nop 0
	global_load_lds_dwordx4 v57, s[0:1]
	v_mfma_f32_16x16x32_bf16 v[72:75], v[144:147], v[156:159], v[72:75]
	v_mfma_f32_16x16x32_bf16 v[48:51], v[144:147], v[160:163], v[48:51]
	s_add_u32 m0, s4, 0x2000
	s_nop 0
	global_load_lds_dwordx4 v58, s[0:1]
	v_mfma_f32_16x16x32_bf16 v[44:47], v[144:147], v[164:167], v[44:47]
	v_mfma_f32_16x16x32_bf16 v[36:39], v[144:147], v[168:171], v[36:39]
	s_add_u32 m0, s4, 0x3000
	s_nop 0
	global_load_lds_dwordx4 v59, s[0:1]
	v_mfma_f32_16x16x32_bf16 v[60:63], v[172:175], v[188:191], v[60:63]
	v_mfma_f32_16x16x32_bf16 v[68:71], v[172:175], v[192:195], v[68:71]
	s_add_u32 m0, s4, 0x4000
	s_nop 0
	global_load_lds_dwordx4 v56, s[2:3]
	v_mfma_f32_16x16x32_bf16 v[52:55], v[172:175], v[196:199], v[52:55]
	v_mfma_f32_16x16x32_bf16 v[40:43], v[172:175], v[200:203], v[40:43]
	s_add_u32 s0, s0, 0x80
	s_addc_u32 s1, s1, 0
	s_add_u32 s2, s2, 0x80
	s_addc_u32 s3, s3, 0
	s_waitcnt vmcnt(10)
	s_barrier
	v_mfma_f32_16x16x32_bf16 v[72:75], v[176:179], v[188:191], v[72:75]
	ds_read_b128 v[220:223], v66 offset:20480
	ds_read_b128 v[224:227], v66 offset:22528
	ds_read_b128 v[236:239], v64 offset:20480
	v_mfma_f32_16x16x32_bf16 v[48:51], v[176:179], v[192:195], v[48:51]
	ds_read_b128 v[240:243], v64 offset:22528
	ds_read_b128 v[244:247], v64 offset:24576
	ds_read_b128 v[248:251], v64 offset:26624
	v_mfma_f32_16x16x32_bf16 v[44:47], v[176:179], v[196:199], v[44:47]
	ds_read_b128 v[112:115], v67 offset:20480
	ds_read_b128 v[116:119], v67 offset:22528
	ds_read_b128 v[76:79], v65 offset:20480
	v_mfma_f32_16x16x32_bf16 v[36:39], v[176:179], v[200:203], v[36:39]
	ds_read_b128 v[80:83], v65 offset:22528
	ds_read_b128 v[84:87], v65 offset:24576
	ds_read_b128 v[88:91], v65 offset:26624
	s_waitcnt lgkmcnt(0)
	s_barrier
	v_mfma_f32_16x16x32_bf16 v[60:63], v[220:223], v[236:239], v[60:63]
	v_mfma_f32_16x16x32_bf16 v[68:71], v[220:223], v[240:243], v[68:71]
	s_add_u32 m0, s4, 0x5000
	s_nop 0
	global_load_lds_dwordx4 v56, s[0:1]
	v_mfma_f32_16x16x32_bf16 v[52:55], v[220:223], v[244:247], v[52:55]
	v_mfma_f32_16x16x32_bf16 v[40:43], v[220:223], v[248:251], v[40:43]
	s_add_u32 m0, s4, 0x6000
	s_nop 0
	global_load_lds_dwordx4 v57, s[0:1]
	v_mfma_f32_16x16x32_bf16 v[72:75], v[224:227], v[236:239], v[72:75]
	v_mfma_f32_16x16x32_bf16 v[48:51], v[224:227], v[240:243], v[48:51]
	s_add_u32 m0, s4, 0x7000
	s_nop 0
	global_load_lds_dwordx4 v58, s[0:1]
	v_mfma_f32_16x16x32_bf16 v[44:47], v[224:227], v[244:247], v[44:47]
	v_mfma_f32_16x16x32_bf16 v[36:39], v[224:227], v[248:251], v[36:39]
	s_add_u32 m0, s4, 0x8000
	s_nop 0
	global_load_lds_dwordx4 v59, s[0:1]
	v_mfma_f32_16x16x32_bf16 v[60:63], v[112:115], v[76:79], v[60:63]
	v_mfma_f32_16x16x32_bf16 v[68:71], v[112:115], v[80:83], v[68:71]
	s_add_u32 m0, s4, 0x9000
	s_nop 0
	global_load_lds_dwordx4 v56, s[2:3]
	v_mfma_f32_16x16x32_bf16 v[52:55], v[112:115], v[84:87], v[52:55]
	v_mfma_f32_16x16x32_bf16 v[40:43], v[112:115], v[88:91], v[40:43]
	s_add_u32 s0, s0, 0x80
	s_addc_u32 s1, s1, 0
	s_add_u32 s2, s2, 0x80
	s_addc_u32 s3, s3, 0
	s_waitcnt vmcnt(10)
	s_barrier
	v_mfma_f32_16x16x32_bf16 v[72:75], v[116:119], v[76:79], v[72:75]
	ds_read_b128 v[140:143], v66 offset:40960
	ds_read_b128 v[144:147], v66 offset:43008
	ds_read_b128 v[156:159], v64 offset:40960
	v_mfma_f32_16x16x32_bf16 v[48:51], v[116:119], v[80:83], v[48:51]
	ds_read_b128 v[160:163], v64 offset:43008
	ds_read_b128 v[164:167], v64 offset:45056
	ds_read_b128 v[168:171], v64 offset:47104
	v_mfma_f32_16x16x32_bf16 v[44:47], v[116:119], v[84:87], v[44:47]
	ds_read_b128 v[172:175], v67 offset:40960
	ds_read_b128 v[176:179], v67 offset:43008
	ds_read_b128 v[188:191], v65 offset:40960
	v_mfma_f32_16x16x32_bf16 v[36:39], v[116:119], v[88:91], v[36:39]
	ds_read_b128 v[192:195], v65 offset:43008
	ds_read_b128 v[196:199], v65 offset:45056
	ds_read_b128 v[200:203], v65 offset:47104
	s_waitcnt lgkmcnt(0)
	s_barrier
	v_mfma_f32_16x16x32_bf16 v[60:63], v[140:143], v[156:159], v[60:63]
	v_mfma_f32_16x16x32_bf16 v[68:71], v[140:143], v[160:163], v[68:71]
	s_add_u32 m0, s4, 0xa000
	s_nop 0
	global_load_lds_dwordx4 v56, s[0:1]
	v_mfma_f32_16x16x32_bf16 v[52:55], v[140:143], v[164:167], v[52:55]
	v_mfma_f32_16x16x32_bf16 v[40:43], v[140:143], v[168:171], v[40:43]
	s_add_u32 m0, s4, 0xb000
	s_nop 0
	global_load_lds_dwordx4 v57, s[0:1]
	v_mfma_f32_16x16x32_bf16 v[72:75], v[144:147], v[156:159], v[72:75]
	v_mfma_f32_16x16x32_bf16 v[48:51], v[144:147], v[160:163], v[48:51]
	s_add_u32 m0, s4, 0xc000
	s_nop 0
	global_load_lds_dwordx4 v58, s[0:1]
	v_mfma_f32_16x16x32_bf16 v[44:47], v[144:147], v[164:167], v[44:47]
	v_mfma_f32_16x16x32_bf16 v[36:39], v[144:147], v[168:171], v[36:39]
	s_add_u32 m0, s4, 0xd000
	s_nop 0
	global_load_lds_dwordx4 v59, s[0:1]
	v_mfma_f32_16x16x32_bf16 v[60:63], v[172:175], v[188:191], v[60:63]
	v_mfma_f32_16x16x32_bf16 v[68:71], v[172:175], v[192:195], v[68:71]
	s_add_u32 m0, s4, 0xe000
	s_nop 0
	global_load_lds_dwordx4 v56, s[2:3]
	v_mfma_f32_16x16x32_bf16 v[52:55], v[172:175], v[196:199], v[52:55]
	v_mfma_f32_16x16x32_bf16 v[40:43], v[172:175], v[200:203], v[40:43]
	s_add_u32 s0, s0, 0x80
	s_addc_u32 s1, s1, 0
	s_add_u32 s2, s2, 0x80
	s_addc_u32 s3, s3, 0
	s_waitcnt vmcnt(10)
	s_barrier
	v_mfma_f32_16x16x32_bf16 v[72:75], v[176:179], v[188:191], v[72:75]
	ds_read_b128 v[220:223], v66 offset:0
	ds_read_b128 v[224:227], v66 offset:2048
	ds_read_b128 v[236:239], v64 offset:0
	v_mfma_f32_16x16x32_bf16 v[48:51], v[176:179], v[192:195], v[48:51]
	ds_read_b128 v[240:243], v64 offset:2048
	ds_read_b128 v[244:247], v64 offset:4096
	ds_read_b128 v[248:251], v64 offset:6144
	v_mfma_f32_16x16x32_bf16 v[44:47], v[176:179], v[196:199], v[44:47]
	ds_read_b128 v[112:115], v67 offset:0
	ds_read_b128 v[116:119], v67 offset:2048
	ds_read_b128 v[76:79], v65 offset:0
	v_mfma_f32_16x16x32_bf16 v[36:39], v[176:179], v[200:203], v[36:39]
	ds_read_b128 v[80:83], v65 offset:2048
	ds_read_b128 v[84:87], v65 offset:4096
	ds_read_b128 v[88:91], v65 offset:6144
	s_waitcnt lgkmcnt(0)
	s_barrier
	v_mfma_f32_16x16x32_bf16 v[60:63], v[220:223], v[236:239], v[60:63]
	v_mfma_f32_16x16x32_bf16 v[68:71], v[220:223], v[240:243], v[68:71]
	s_add_u32 m0, s4, 0x0
	s_nop 0
	global_load_lds_dwordx4 v56, s[0:1]
	v_mfma_f32_16x16x32_bf16 v[52:55], v[220:223], v[244:247], v[52:55]
	v_mfma_f32_16x16x32_bf16 v[40:43], v[220:223], v[248:251], v[40:43]
	s_add_u32 m0, s4, 0x1000
	s_nop 0
	global_load_lds_dwordx4 v57, s[0:1]
	v_mfma_f32_16x16x32_bf16 v[72:75], v[224:227], v[236:239], v[72:75]
	v_mfma_f32_16x16x32_bf16 v[48:51], v[224:227], v[240:243], v[48:51]
	s_add_u32 m0, s4, 0x2000
	s_nop 0
	global_load_lds_dwordx4 v58, s[0:1]
	v_mfma_f32_16x16x32_bf16 v[44:47], v[224:227], v[244:247], v[44:47]
	v_mfma_f32_16x16x32_bf16 v[36:39], v[224:227], v[248:251], v[36:39]
	s_add_u32 m0, s4, 0x3000
	s_nop 0
	global_load_lds_dwordx4 v59, s[0:1]
	v_mfma_f32_16x16x32_bf16 v[60:63], v[112:115], v[76:79], v[60:63]
	v_mfma_f32_16x16x32_bf16 v[68:71], v[112:115], v[80:83], v[68:71]
	s_add_u32 m0, s4, 0x4000
	s_nop 0
	global_load_lds_dwordx4 v56, s[2:3]
	v_mfma_f32_16x16x32_bf16 v[52:55], v[112:115], v[84:87], v[52:55]
	v_mfma_f32_16x16x32_bf16 v[40:43], v[112:115], v[88:91], v[40:43]
	s_add_u32 s0, s0, 0x80
	s_addc_u32 s1, s1, 0
	s_add_u32 s2, s2, 0x80
	s_addc_u32 s3, s3, 0
	s_waitcnt vmcnt(10)
	s_barrier
	v_mfma_f32_16x16x32_bf16 v[72:75], v[116:119], v[76:79], v[72:75]
	ds_read_b128 v[140:143], v66 offset:20480
	ds_read_b128 v[144:147], v66 offset:22528
	ds_read_b128 v[156:159], v64 offset:20480
	v_mfma_f32_16x16x32_bf16 v[48:51], v[116:119], v[80:83], v[48:51]
	ds_read_b128 v[160:163], v64 offset:22528
	ds_read_b128 v[164:167], v64 offset:24576
	ds_read_b128 v[168:171], v64 offset:26624
	v_mfma_f32_16x16x32_bf16 v[44:47], v[116:119], v[84:87], v[44:47]
	ds_read_b128 v[172:175], v67 offset:20480
	ds_read_b128 v[176:179], v67 offset:22528
	ds_read_b128 v[188:191], v65 offset:20480
	v_mfma_f32_16x16x32_bf16 v[36:39], v[116:119], v[88:91], v[36:39]
	ds_read_b128 v[192:195], v65 offset:22528
	ds_read_b128 v[196:199], v65 offset:24576
	ds_read_b128 v[200:203], v65 offset:26624
	s_waitcnt lgkmcnt(0)
	s_barrier
	v_mfma_f32_16x16x32_bf16 v[60:63], v[140:143], v[156:159], v[60:63]
	v_mfma_f32_16x16x32_bf16 v[68:71], v[140:143], v[160:163], v[68:71]
	s_add_u32 m0, s4, 0x5000
	s_nop 0
	global_load_lds_dwordx4 v56, s[0:1]
	v_mfma_f32_16x16x32_bf16 v[52:55], v[140:143], v[164:167], v[52:55]
	v_mfma_f32_16x16x32_bf16 v[40:43], v[140:143], v[168:171], v[40:43]
	s_add_u32 m0, s4, 0x6000
	s_nop 0
	global_load_lds_dwordx4 v57, s[0:1]
	v_mfma_f32_16x16x32_bf16 v[72:75], v[144:147], v[156:159], v[72:75]
	v_mfma_f32_16x16x32_bf16 v[48:51], v[144:147], v[160:163], v[48:51]
	s_add_u32 m0, s4, 0x7000
	s_nop 0
	global_load_lds_dwordx4 v58, s[0:1]
	v_mfma_f32_16x16x32_bf16 v[44:47], v[144:147], v[164:167], v[44:47]
	v_mfma_f32_16x16x32_bf16 v[36:39], v[144:147], v[168:171], v[36:39]
	s_add_u32 m0, s4, 0x8000
	s_nop 0
	global_load_lds_dwordx4 v59, s[0:1]
	v_mfma_f32_16x16x32_bf16 v[60:63], v[172:175], v[188:191], v[60:63]
	v_mfma_f32_16x16x32_bf16 v[68:71], v[172:175], v[192:195], v[68:71]
	s_add_u32 m0, s4, 0x9000
	s_nop 0
	global_load_lds_dwordx4 v56, s[2:3]
	v_mfma_f32_16x16x32_bf16 v[52:55], v[172:175], v[196:199], v[52:55]
	v_mfma_f32_16x16x32_bf16 v[40:43], v[172:175], v[200:203], v[40:43]
	s_add_u32 s0, s0, 0x80
	s_addc_u32 s1, s1, 0
	s_add_u32 s2, s2, 0x80
	s_addc_u32 s3, s3, 0
	s_waitcnt vmcnt(10)
	s_barrier
	v_mfma_f32_16x16x32_bf16 v[72:75], v[176:179], v[188:191], v[72:75]
	ds_read_b128 v[220:223], v66 offset:40960
	ds_read_b128 v[224:227], v66 offset:43008
	ds_read_b128 v[236:239], v64 offset:40960
	v_mfma_f32_16x16x32_bf16 v[48:51], v[176:179], v[192:195], v[48:51]
	ds_read_b128 v[240:243], v64 offset:43008
	ds_read_b128 v[244:247], v64 offset:45056
	ds_read_b128 v[248:251], v64 offset:47104
	v_mfma_f32_16x16x32_bf16 v[44:47], v[176:179], v[196:199], v[44:47]
	ds_read_b128 v[112:115], v67 offset:40960
	ds_read_b128 v[116:119], v67 offset:43008
	ds_read_b128 v[76:79], v65 offset:40960
	v_mfma_f32_16x16x32_bf16 v[36:39], v[176:179], v[200:203], v[36:39]
	ds_read_b128 v[80:83], v65 offset:43008
	ds_read_b128 v[84:87], v65 offset:45056
	ds_read_b128 v[88:91], v65 offset:47104
	s_waitcnt lgkmcnt(0)
	s_barrier
	v_mfma_f32_16x16x32_bf16 v[60:63], v[220:223], v[236:239], v[60:63]
	v_mfma_f32_16x16x32_bf16 v[68:71], v[220:223], v[240:243], v[68:71]
	s_add_u32 m0, s4, 0xa000
	s_nop 0
	global_load_lds_dwordx4 v56, s[0:1]
	v_mfma_f32_16x16x32_bf16 v[52:55], v[220:223], v[244:247], v[52:55]
	v_mfma_f32_16x16x32_bf16 v[40:43], v[220:223], v[248:251], v[40:43]
	s_add_u32 m0, s4, 0xb000
	s_nop 0
	global_load_lds_dwordx4 v57, s[0:1]
	v_mfma_f32_16x16x32_bf16 v[72:75], v[224:227], v[236:239], v[72:75]
	v_mfma_f32_16x16x32_bf16 v[48:51], v[224:227], v[240:243], v[48:51]
	s_add_u32 m0, s4, 0xc000
	s_nop 0
	global_load_lds_dwordx4 v58, s[0:1]
	v_mfma_f32_16x16x32_bf16 v[44:47], v[224:227], v[244:247], v[44:47]
	v_mfma_f32_16x16x32_bf16 v[36:39], v[224:227], v[248:251], v[36:39]
	s_add_u32 m0, s4, 0xd000
	s_nop 0
	global_load_lds_dwordx4 v59, s[0:1]
	v_mfma_f32_16x16x32_bf16 v[60:63], v[112:115], v[76:79], v[60:63]
	v_mfma_f32_16x16x32_bf16 v[68:71], v[112:115], v[80:83], v[68:71]
	s_add_u32 m0, s4, 0xe000
	s_nop 0
	global_load_lds_dwordx4 v56, s[2:3]
	v_mfma_f32_16x16x32_bf16 v[52:55], v[112:115], v[84:87], v[52:55]
	v_mfma_f32_16x16x32_bf16 v[40:43], v[112:115], v[88:91], v[40:43]
	s_add_u32 s0, s0, 0x80
	s_addc_u32 s1, s1, 0
	s_add_u32 s2, s2, 0x80
	s_addc_u32 s3, s3, 0
	s_waitcnt vmcnt(10)
	s_barrier
	v_mfma_f32_16x16x32_bf16 v[72:75], v[116:119], v[76:79], v[72:75]
	ds_read_b128 v[140:143], v66 offset:0
	ds_read_b128 v[144:147], v66 offset:2048
	ds_read_b128 v[156:159], v64 offset:0
	v_mfma_f32_16x16x32_bf16 v[48:51], v[116:119], v[80:83], v[48:51]
	ds_read_b128 v[160:163], v64 offset:2048
	ds_read_b128 v[164:167], v64 offset:4096
	ds_read_b128 v[168:171], v64 offset:6144
	v_mfma_f32_16x16x32_bf16 v[44:47], v[116:119], v[84:87], v[44:47]
	ds_read_b128 v[172:175], v67 offset:0
	ds_read_b128 v[176:179], v67 offset:2048
	ds_read_b128 v[188:191], v65 offset:0
	v_mfma_f32_16x16x32_bf16 v[36:39], v[116:119], v[88:91], v[36:39]
	ds_read_b128 v[192:195], v65 offset:2048
	ds_read_b128 v[196:199], v65 offset:4096
	ds_read_b128 v[200:203], v65 offset:6144
	s_waitcnt lgkmcnt(0)
	s_barrier
	v_mfma_f32_16x16x32_bf16 v[60:63], v[140:143], v[156:159], v[60:63]
	v_mfma_f32_16x16x32_bf16 v[68:71], v[140:143], v[160:163], v[68:71]
	s_add_u32 m0, s4, 0x0
	s_nop 0
	global_load_lds_dwordx4 v56, s[0:1]
	v_mfma_f32_16x16x32_bf16 v[52:55], v[140:143], v[164:167], v[52:55]
	v_mfma_f32_16x16x32_bf16 v[40:43], v[140:143], v[168:171], v[40:43]
	s_add_u32 m0, s4, 0x1000
	s_nop 0
	global_load_lds_dwordx4 v57, s[0:1]
	v_mfma_f32_16x16x32_bf16 v[72:75], v[144:147], v[156:159], v[72:75]
	v_mfma_f32_16x16x32_bf16 v[48:51], v[144:147], v[160:163], v[48:51]
	s_add_u32 m0, s4, 0x2000
	s_nop 0
	global_load_lds_dwordx4 v58, s[0:1]
	v_mfma_f32_16x16x32_bf16 v[44:47], v[144:147], v[164:167], v[44:47]
	v_mfma_f32_16x16x32_bf16 v[36:39], v[144:147], v[168:171], v[36:39]
	s_add_u32 m0, s4, 0x3000
	s_nop 0
	global_load_lds_dwordx4 v59, s[0:1]
	v_mfma_f32_16x16x32_bf16 v[60:63], v[172:175], v[188:191], v[60:63]
	v_mfma_f32_16x16x32_bf16 v[68:71], v[172:175], v[192:195], v[68:71]
	s_add_u32 m0, s4, 0x4000
	s_nop 0
	global_load_lds_dwordx4 v56, s[2:3]
	v_mfma_f32_16x16x32_bf16 v[52:55], v[172:175], v[196:199], v[52:55]
	v_mfma_f32_16x16x32_bf16 v[40:43], v[172:175], v[200:203], v[40:43]
	s_add_u32 s0, s0, 0x80
	s_addc_u32 s1, s1, 0
	s_add_u32 s2, s2, 0x80
	s_addc_u32 s3, s3, 0
	s_waitcnt vmcnt(10)
	s_barrier
	v_mfma_f32_16x16x32_bf16 v[72:75], v[176:179], v[188:191], v[72:75]
	ds_read_b128 v[220:223], v66 offset:20480
	ds_read_b128 v[224:227], v66 offset:22528
	ds_read_b128 v[236:239], v64 offset:20480
	v_mfma_f32_16x16x32_bf16 v[48:51], v[176:179], v[192:195], v[48:51]
	ds_read_b128 v[240:243], v64 offset:22528
	ds_read_b128 v[244:247], v64 offset:24576
	ds_read_b128 v[248:251], v64 offset:26624
	v_mfma_f32_16x16x32_bf16 v[44:47], v[176:179], v[196:199], v[44:47]
	ds_read_b128 v[112:115], v67 offset:20480
	ds_read_b128 v[116:119], v67 offset:22528
	ds_read_b128 v[76:79], v65 offset:20480
	v_mfma_f32_16x16x32_bf16 v[36:39], v[176:179], v[200:203], v[36:39]
	ds_read_b128 v[80:83], v65 offset:22528
	ds_read_b128 v[84:87], v65 offset:24576
	ds_read_b128 v[88:91], v65 offset:26624
	s_waitcnt lgkmcnt(0)
	s_barrier
	v_mfma_f32_16x16x32_bf16 v[60:63], v[220:223], v[236:239], v[60:63]
	v_mfma_f32_16x16x32_bf16 v[68:71], v[220:223], v[240:243], v[68:71]
	s_add_u32 m0, s4, 0x5000
	s_nop 0
	global_load_lds_dwordx4 v56, s[0:1]
	v_mfma_f32_16x16x32_bf16 v[52:55], v[220:223], v[244:247], v[52:55]
	v_mfma_f32_16x16x32_bf16 v[40:43], v[220:223], v[248:251], v[40:43]
	s_add_u32 m0, s4, 0x6000
	s_nop 0
	global_load_lds_dwordx4 v57, s[0:1]
	v_mfma_f32_16x16x32_bf16 v[72:75], v[224:227], v[236:239], v[72:75]
	v_mfma_f32_16x16x32_bf16 v[48:51], v[224:227], v[240:243], v[48:51]
	s_add_u32 m0, s4, 0x7000
	s_nop 0
	global_load_lds_dwordx4 v58, s[0:1]
	v_mfma_f32_16x16x32_bf16 v[44:47], v[224:227], v[244:247], v[44:47]
	v_mfma_f32_16x16x32_bf16 v[36:39], v[224:227], v[248:251], v[36:39]
	s_add_u32 m0, s4, 0x8000
	s_nop 0
	global_load_lds_dwordx4 v59, s[0:1]
	v_mfma_f32_16x16x32_bf16 v[60:63], v[112:115], v[76:79], v[60:63]
	v_mfma_f32_16x16x32_bf16 v[68:71], v[112:115], v[80:83], v[68:71]
	s_add_u32 m0, s4, 0x9000
	s_nop 0
	global_load_lds_dwordx4 v56, s[2:3]
	v_mfma_f32_16x16x32_bf16 v[52:55], v[112:115], v[84:87], v[52:55]
	v_mfma_f32_16x16x32_bf16 v[40:43], v[112:115], v[88:91], v[40:43]
	s_add_u32 s0, s0, 0x80
	s_addc_u32 s1, s1, 0
	s_add_u32 s2, s2, 0x80
	s_addc_u32 s3, s3, 0
	s_waitcnt vmcnt(10)
	s_barrier
	v_mfma_f32_16x16x32_bf16 v[72:75], v[116:119], v[76:79], v[72:75]
	ds_read_b128 v[140:143], v66 offset:40960
	ds_read_b128 v[144:147], v66 offset:43008
	ds_read_b128 v[156:159], v64 offset:40960
	v_mfma_f32_16x16x32_bf16 v[48:51], v[116:119], v[80:83], v[48:51]
	ds_read_b128 v[160:163], v64 offset:43008
	ds_read_b128 v[164:167], v64 offset:45056
	ds_read_b128 v[168:171], v64 offset:47104
	v_mfma_f32_16x16x32_bf16 v[44:47], v[116:119], v[84:87], v[44:47]
	ds_read_b128 v[172:175], v67 offset:40960
	ds_read_b128 v[176:179], v67 offset:43008
	ds_read_b128 v[188:191], v65 offset:40960
	v_mfma_f32_16x16x32_bf16 v[36:39], v[116:119], v[88:91], v[36:39]
	ds_read_b128 v[192:195], v65 offset:43008
	ds_read_b128 v[196:199], v65 offset:45056
	ds_read_b128 v[200:203], v65 offset:47104
	s_waitcnt lgkmcnt(0)
	s_barrier
	v_mfma_f32_16x16x32_bf16 v[60:63], v[140:143], v[156:159], v[60:63]
	v_mfma_f32_16x16x32_bf16 v[68:71], v[140:143], v[160:163], v[68:71]
	s_add_u32 m0, s4, 0xa000
	s_nop 0
	global_load_lds_dwordx4 v56, s[0:1]
	v_mfma_f32_16x16x32_bf16 v[52:55], v[140:143], v[164:167], v[52:55]
	v_mfma_f32_16x16x32_bf16 v[40:43], v[140:143], v[168:171], v[40:43]
	s_add_u32 m0, s4, 0xb000
	s_nop 0
	global_load_lds_dwordx4 v57, s[0:1]
	v_mfma_f32_16x16x32_bf16 v[72:75], v[144:147], v[156:159], v[72:75]
	v_mfma_f32_16x16x32_bf16 v[48:51], v[144:147], v[160:163], v[48:51]
	s_add_u32 m0, s4, 0xc000
	s_nop 0
	global_load_lds_dwordx4 v58, s[0:1]
	v_mfma_f32_16x16x32_bf16 v[44:47], v[144:147], v[164:167], v[44:47]
	v_mfma_f32_16x16x32_bf16 v[36:39], v[144:147], v[168:171], v[36:39]
	s_add_u32 m0, s4, 0xd000
	s_nop 0
	global_load_lds_dwordx4 v59, s[0:1]
	v_mfma_f32_16x16x32_bf16 v[60:63], v[172:175], v[188:191], v[60:63]
	v_mfma_f32_16x16x32_bf16 v[68:71], v[172:175], v[192:195], v[68:71]
	s_add_u32 m0, s4, 0xe000
	s_nop 0
	global_load_lds_dwordx4 v56, s[2:3]
	v_mfma_f32_16x16x32_bf16 v[52:55], v[172:175], v[196:199], v[52:55]
	v_mfma_f32_16x16x32_bf16 v[40:43], v[172:175], v[200:203], v[40:43]
	s_add_u32 s0, s0, 0x80
	s_addc_u32 s1, s1, 0
	s_add_u32 s2, s2, 0x80
	s_addc_u32 s3, s3, 0
	s_waitcnt vmcnt(10)
	s_barrier
	v_mfma_f32_16x16x32_bf16 v[72:75], v[176:179], v[188:191], v[72:75]
	ds_read_b128 v[220:223], v66 offset:0
	ds_read_b128 v[224:227], v66 offset:2048
	ds_read_b128 v[236:239], v64 offset:0
	v_mfma_f32_16x16x32_bf16 v[48:51], v[176:179], v[192:195], v[48:51]
	ds_read_b128 v[240:243], v64 offset:2048
	ds_read_b128 v[244:247], v64 offset:4096
	ds_read_b128 v[248:251], v64 offset:6144
	v_mfma_f32_16x16x32_bf16 v[44:47], v[176:179], v[196:199], v[44:47]
	ds_read_b128 v[112:115], v67 offset:0
	ds_read_b128 v[116:119], v67 offset:2048
	ds_read_b128 v[76:79], v65 offset:0
	v_mfma_f32_16x16x32_bf16 v[36:39], v[176:179], v[200:203], v[36:39]
	ds_read_b128 v[80:83], v65 offset:2048
	ds_read_b128 v[84:87], v65 offset:4096
	ds_read_b128 v[88:91], v65 offset:6144
	s_waitcnt lgkmcnt(0)
	s_barrier
	v_mfma_f32_16x16x32_bf16 v[60:63], v[220:223], v[236:239], v[60:63]
	v_mfma_f32_16x16x32_bf16 v[68:71], v[220:223], v[240:243], v[68:71]
	s_add_u32 m0, s4, 0x0
	s_nop 0
	global_load_lds_dwordx4 v56, s[0:1]
	v_mfma_f32_16x16x32_bf16 v[52:55], v[220:223], v[244:247], v[52:55]
	v_mfma_f32_16x16x32_bf16 v[40:43], v[220:223], v[248:251], v[40:43]
	s_add_u32 m0, s4, 0x1000
	s_nop 0
	global_load_lds_dwordx4 v57, s[0:1]
	v_mfma_f32_16x16x32_bf16 v[72:75], v[224:227], v[236:239], v[72:75]
	v_mfma_f32_16x16x32_bf16 v[48:51], v[224:227], v[240:243], v[48:51]
	s_add_u32 m0, s4, 0x2000
	s_nop 0
	global_load_lds_dwordx4 v58, s[0:1]
	v_mfma_f32_16x16x32_bf16 v[44:47], v[224:227], v[244:247], v[44:47]
	v_mfma_f32_16x16x32_bf16 v[36:39], v[224:227], v[248:251], v[36:39]
	s_add_u32 m0, s4, 0x3000
	s_nop 0
	global_load_lds_dwordx4 v59, s[0:1]
	v_mfma_f32_16x16x32_bf16 v[60:63], v[112:115], v[76:79], v[60:63]
	v_mfma_f32_16x16x32_bf16 v[68:71], v[112:115], v[80:83], v[68:71]
	s_add_u32 m0, s4, 0x4000
	s_nop 0
	global_load_lds_dwordx4 v56, s[2:3]
	v_mfma_f32_16x16x32_bf16 v[52:55], v[112:115], v[84:87], v[52:55]
	v_mfma_f32_16x16x32_bf16 v[40:43], v[112:115], v[88:91], v[40:43]
	s_add_u32 s0, s0, 0x80
	s_addc_u32 s1, s1, 0
	s_add_u32 s2, s2, 0x80
	s_addc_u32 s3, s3, 0
	s_waitcnt vmcnt(10)
	s_barrier
	v_mfma_f32_16x16x32_bf16 v[72:75], v[116:119], v[76:79], v[72:75]
	ds_read_b128 v[140:143], v66 offset:20480
	ds_read_b128 v[144:147], v66 offset:22528
	ds_read_b128 v[156:159], v64 offset:20480
	v_mfma_f32_16x16x32_bf16 v[48:51], v[116:119], v[80:83], v[48:51]
	ds_read_b128 v[160:163], v64 offset:22528
	ds_read_b128 v[164:167], v64 offset:24576
	ds_read_b128 v[168:171], v64 offset:26624
	v_mfma_f32_16x16x32_bf16 v[44:47], v[116:119], v[84:87], v[44:47]
	ds_read_b128 v[172:175], v67 offset:20480
	ds_read_b128 v[176:179], v67 offset:22528
	ds_read_b128 v[188:191], v65 offset:20480
	v_mfma_f32_16x16x32_bf16 v[36:39], v[116:119], v[88:91], v[36:39]
	ds_read_b128 v[192:195], v65 offset:22528
	ds_read_b128 v[196:199], v65 offset:24576
	ds_read_b128 v[200:203], v65 offset:26624
	s_waitcnt lgkmcnt(0)
	s_barrier
	v_mfma_f32_16x16x32_bf16 v[60:63], v[140:143], v[156:159], v[60:63]
	v_mfma_f32_16x16x32_bf16 v[68:71], v[140:143], v[160:163], v[68:71]
	s_add_u32 m0, s4, 0x5000
	s_nop 0
	global_load_lds_dwordx4 v56, s[0:1]
	v_mfma_f32_16x16x32_bf16 v[52:55], v[140:143], v[164:167], v[52:55]
	v_mfma_f32_16x16x32_bf16 v[40:43], v[140:143], v[168:171], v[40:43]
	s_add_u32 m0, s4, 0x6000
	s_nop 0
	global_load_lds_dwordx4 v57, s[0:1]
	v_mfma_f32_16x16x32_bf16 v[72:75], v[144:147], v[156:159], v[72:75]
	v_mfma_f32_16x16x32_bf16 v[48:51], v[144:147], v[160:163], v[48:51]
	s_add_u32 m0, s4, 0x7000
	s_nop 0
	global_load_lds_dwordx4 v58, s[0:1]
	v_mfma_f32_16x16x32_bf16 v[44:47], v[144:147], v[164:167], v[44:47]
	v_mfma_f32_16x16x32_bf16 v[36:39], v[144:147], v[168:171], v[36:39]
	s_add_u32 m0, s4, 0x8000
	s_nop 0
	global_load_lds_dwordx4 v59, s[0:1]
	v_mfma_f32_16x16x32_bf16 v[60:63], v[172:175], v[188:191], v[60:63]
	v_mfma_f32_16x16x32_bf16 v[68:71], v[172:175], v[192:195], v[68:71]
	s_add_u32 m0, s4, 0x9000
	s_nop 0
	global_load_lds_dwordx4 v56, s[2:3]
	v_mfma_f32_16x16x32_bf16 v[52:55], v[172:175], v[196:199], v[52:55]
	v_mfma_f32_16x16x32_bf16 v[40:43], v[172:175], v[200:203], v[40:43]
	s_add_u32 s0, s0, 0x80
	s_addc_u32 s1, s1, 0
	s_add_u32 s2, s2, 0x80
	s_addc_u32 s3, s3, 0
	s_waitcnt vmcnt(10)
	s_barrier
	v_mfma_f32_16x16x32_bf16 v[72:75], v[176:179], v[188:191], v[72:75]
	ds_read_b128 v[220:223], v66 offset:40960
	ds_read_b128 v[224:227], v66 offset:43008
	ds_read_b128 v[236:239], v64 offset:40960
	v_mfma_f32_16x16x32_bf16 v[48:51], v[176:179], v[192:195], v[48:51]
	ds_read_b128 v[240:243], v64 offset:43008
	ds_read_b128 v[244:247], v64 offset:45056
	ds_read_b128 v[248:251], v64 offset:47104
	v_mfma_f32_16x16x32_bf16 v[44:47], v[176:179], v[196:199], v[44:47]
	ds_read_b128 v[112:115], v67 offset:40960
	ds_read_b128 v[116:119], v67 offset:43008
	ds_read_b128 v[76:79], v65 offset:40960
	v_mfma_f32_16x16x32_bf16 v[36:39], v[176:179], v[200:203], v[36:39]
	ds_read_b128 v[80:83], v65 offset:43008
	ds_read_b128 v[84:87], v65 offset:45056
	ds_read_b128 v[88:91], v65 offset:47104
	s_waitcnt lgkmcnt(0)
	s_barrier
	v_mfma_f32_16x16x32_bf16 v[60:63], v[220:223], v[236:239], v[60:63]
	v_mfma_f32_16x16x32_bf16 v[68:71], v[220:223], v[240:243], v[68:71]
	s_add_u32 m0, s4, 0xa000
	s_nop 0
	global_load_lds_dwordx4 v56, s[0:1]
	v_mfma_f32_16x16x32_bf16 v[52:55], v[220:223], v[244:247], v[52:55]
	v_mfma_f32_16x16x32_bf16 v[40:43], v[220:223], v[248:251], v[40:43]
	s_add_u32 m0, s4, 0xb000
	s_nop 0
	global_load_lds_dwordx4 v57, s[0:1]
	v_mfma_f32_16x16x32_bf16 v[72:75], v[224:227], v[236:239], v[72:75]
	v_mfma_f32_16x16x32_bf16 v[48:51], v[224:227], v[240:243], v[48:51]
	s_add_u32 m0, s4, 0xc000
	s_nop 0
	global_load_lds_dwordx4 v58, s[0:1]
	v_mfma_f32_16x16x32_bf16 v[44:47], v[224:227], v[244:247], v[44:47]
	v_mfma_f32_16x16x32_bf16 v[36:39], v[224:227], v[248:251], v[36:39]
	s_add_u32 m0, s4, 0xd000
	s_nop 0
	global_load_lds_dwordx4 v59, s[0:1]
	v_mfma_f32_16x16x32_bf16 v[60:63], v[112:115], v[76:79], v[60:63]
	v_mfma_f32_16x16x32_bf16 v[68:71], v[112:115], v[80:83], v[68:71]
	s_add_u32 m0, s4, 0xe000
	s_nop 0
	global_load_lds_dwordx4 v56, s[2:3]
	v_mfma_f32_16x16x32_bf16 v[52:55], v[112:115], v[84:87], v[52:55]
	v_mfma_f32_16x16x32_bf16 v[40:43], v[112:115], v[88:91], v[40:43]
	s_add_u32 s0, s0, 0x80
	s_addc_u32 s1, s1, 0
	s_add_u32 s2, s2, 0x80
	s_addc_u32 s3, s3, 0
	s_waitcnt vmcnt(10)
	s_barrier
	v_mfma_f32_16x16x32_bf16 v[72:75], v[116:119], v[76:79], v[72:75]
	ds_read_b128 v[140:143], v66 offset:0
	ds_read_b128 v[144:147], v66 offset:2048
	ds_read_b128 v[156:159], v64 offset:0
	v_mfma_f32_16x16x32_bf16 v[48:51], v[116:119], v[80:83], v[48:51]
	ds_read_b128 v[160:163], v64 offset:2048
	ds_read_b128 v[164:167], v64 offset:4096
	ds_read_b128 v[168:171], v64 offset:6144
	v_mfma_f32_16x16x32_bf16 v[44:47], v[116:119], v[84:87], v[44:47]
	ds_read_b128 v[172:175], v67 offset:0
	ds_read_b128 v[176:179], v67 offset:2048
	ds_read_b128 v[188:191], v65 offset:0
	v_mfma_f32_16x16x32_bf16 v[36:39], v[116:119], v[88:91], v[36:39]
	ds_read_b128 v[192:195], v65 offset:2048
	ds_read_b128 v[196:199], v65 offset:4096
	ds_read_b128 v[200:203], v65 offset:6144
	s_waitcnt lgkmcnt(0)
	s_barrier
	v_mfma_f32_16x16x32_bf16 v[60:63], v[140:143], v[156:159], v[60:63]
	v_mfma_f32_16x16x32_bf16 v[68:71], v[140:143], v[160:163], v[68:71]
	s_add_u32 m0, s4, 0x0
	s_nop 0
	global_load_lds_dwordx4 v56, s[0:1]
	v_mfma_f32_16x16x32_bf16 v[52:55], v[140:143], v[164:167], v[52:55]
	v_mfma_f32_16x16x32_bf16 v[40:43], v[140:143], v[168:171], v[40:43]
	s_add_u32 m0, s4, 0x1000
	s_nop 0
	global_load_lds_dwordx4 v57, s[0:1]
	v_mfma_f32_16x16x32_bf16 v[72:75], v[144:147], v[156:159], v[72:75]
	v_mfma_f32_16x16x32_bf16 v[48:51], v[144:147], v[160:163], v[48:51]
	s_add_u32 m0, s4, 0x2000
	s_nop 0
	global_load_lds_dwordx4 v58, s[0:1]
	v_mfma_f32_16x16x32_bf16 v[44:47], v[144:147], v[164:167], v[44:47]
	v_mfma_f32_16x16x32_bf16 v[36:39], v[144:147], v[168:171], v[36:39]
	s_add_u32 m0, s4, 0x3000
	s_nop 0
	global_load_lds_dwordx4 v59, s[0:1]
	v_mfma_f32_16x16x32_bf16 v[60:63], v[172:175], v[188:191], v[60:63]
	v_mfma_f32_16x16x32_bf16 v[68:71], v[172:175], v[192:195], v[68:71]
	s_add_u32 m0, s4, 0x4000
	s_nop 0
	global_load_lds_dwordx4 v56, s[2:3]
	v_mfma_f32_16x16x32_bf16 v[52:55], v[172:175], v[196:199], v[52:55]
	v_mfma_f32_16x16x32_bf16 v[40:43], v[172:175], v[200:203], v[40:43]
	s_add_u32 s0, s0, 0x80
	s_addc_u32 s1, s1, 0
	s_add_u32 s2, s2, 0x80
	s_addc_u32 s3, s3, 0
	s_waitcnt vmcnt(10)
	s_barrier
	v_mfma_f32_16x16x32_bf16 v[72:75], v[176:179], v[188:191], v[72:75]
	ds_read_b128 v[220:223], v66 offset:20480
	ds_read_b128 v[224:227], v66 offset:22528
	ds_read_b128 v[236:239], v64 offset:20480
	v_mfma_f32_16x16x32_bf16 v[48:51], v[176:179], v[192:195], v[48:51]
	ds_read_b128 v[240:243], v64 offset:22528
	ds_read_b128 v[244:247], v64 offset:24576
	ds_read_b128 v[248:251], v64 offset:26624
	v_mfma_f32_16x16x32_bf16 v[44:47], v[176:179], v[196:199], v[44:47]
	ds_read_b128 v[112:115], v67 offset:20480
	ds_read_b128 v[116:119], v67 offset:22528
	ds_read_b128 v[76:79], v65 offset:20480
	v_mfma_f32_16x16x32_bf16 v[36:39], v[176:179], v[200:203], v[36:39]
	ds_read_b128 v[80:83], v65 offset:22528
	ds_read_b128 v[84:87], v65 offset:24576
	ds_read_b128 v[88:91], v65 offset:26624
	s_waitcnt lgkmcnt(0)
	s_barrier
	v_mfma_f32_16x16x32_bf16 v[60:63], v[220:223], v[236:239], v[60:63]
	v_mfma_f32_16x16x32_bf16 v[68:71], v[220:223], v[240:243], v[68:71]
	v_mfma_f32_16x16x32_bf16 v[52:55], v[220:223], v[244:247], v[52:55]
	v_mfma_f32_16x16x32_bf16 v[40:43], v[220:223], v[248:251], v[40:43]
	v_mfma_f32_16x16x32_bf16 v[72:75], v[224:227], v[236:239], v[72:75]
	v_mfma_f32_16x16x32_bf16 v[48:51], v[224:227], v[240:243], v[48:51]
	v_mfma_f32_16x16x32_bf16 v[44:47], v[224:227], v[244:247], v[44:47]
	v_mfma_f32_16x16x32_bf16 v[36:39], v[224:227], v[248:251], v[36:39]
	v_mfma_f32_16x16x32_bf16 v[60:63], v[112:115], v[76:79], v[60:63]
	v_mfma_f32_16x16x32_bf16 v[68:71], v[112:115], v[80:83], v[68:71]
	v_mfma_f32_16x16x32_bf16 v[52:55], v[112:115], v[84:87], v[52:55]
	v_mfma_f32_16x16x32_bf16 v[40:43], v[112:115], v[88:91], v[40:43]
	s_waitcnt vmcnt(5)
	s_barrier
	v_mfma_f32_16x16x32_bf16 v[72:75], v[116:119], v[76:79], v[72:75]
	ds_read_b128 v[140:143], v66 offset:40960
	ds_read_b128 v[144:147], v66 offset:43008
	ds_read_b128 v[156:159], v64 offset:40960
	v_mfma_f32_16x16x32_bf16 v[48:51], v[116:119], v[80:83], v[48:51]
	ds_read_b128 v[160:163], v64 offset:43008
	ds_read_b128 v[164:167], v64 offset:45056
	ds_read_b128 v[168:171], v64 offset:47104
	v_mfma_f32_16x16x32_bf16 v[44:47], v[116:119], v[84:87], v[44:47]
	ds_read_b128 v[172:175], v67 offset:40960
	ds_read_b128 v[176:179], v67 offset:43008
	ds_read_b128 v[188:191], v65 offset:40960
	v_mfma_f32_16x16x32_bf16 v[36:39], v[116:119], v[88:91], v[36:39]
	ds_read_b128 v[192:195], v65 offset:43008
	ds_read_b128 v[196:199], v65 offset:45056
	ds_read_b128 v[200:203], v65 offset:47104
	s_waitcnt lgkmcnt(0)
	s_barrier
	v_mfma_f32_16x16x32_bf16 v[60:63], v[140:143], v[156:159], v[60:63]
	v_mfma_f32_16x16x32_bf16 v[68:71], v[140:143], v[160:163], v[68:71]
	v_mfma_f32_16x16x32_bf16 v[52:55], v[140:143], v[164:167], v[52:55]
	v_mfma_f32_16x16x32_bf16 v[40:43], v[140:143], v[168:171], v[40:43]
	v_mfma_f32_16x16x32_bf16 v[72:75], v[144:147], v[156:159], v[72:75]
	v_mfma_f32_16x16x32_bf16 v[48:51], v[144:147], v[160:163], v[48:51]
	v_mfma_f32_16x16x32_bf16 v[44:47], v[144:147], v[164:167], v[44:47]
	v_mfma_f32_16x16x32_bf16 v[36:39], v[144:147], v[168:171], v[36:39]
	v_mfma_f32_16x16x32_bf16 v[60:63], v[172:175], v[188:191], v[60:63]
	v_mfma_f32_16x16x32_bf16 v[68:71], v[172:175], v[192:195], v[68:71]
	v_mfma_f32_16x16x32_bf16 v[52:55], v[172:175], v[196:199], v[52:55]
	v_mfma_f32_16x16x32_bf16 v[40:43], v[172:175], v[200:203], v[40:43]
	s_waitcnt vmcnt(0)
	s_barrier
	v_mfma_f32_16x16x32_bf16 v[72:75], v[176:179], v[188:191], v[72:75]
	ds_read_b128 v[220:223], v66 offset:0
	ds_read_b128 v[224:227], v66 offset:2048
	ds_read_b128 v[236:239], v64 offset:0
	v_mfma_f32_16x16x32_bf16 v[48:51], v[176:179], v[192:195], v[48:51]
	ds_read_b128 v[240:243], v64 offset:2048
	ds_read_b128 v[244:247], v64 offset:4096
	ds_read_b128 v[248:251], v64 offset:6144
	v_mfma_f32_16x16x32_bf16 v[44:47], v[176:179], v[196:199], v[44:47]
	ds_read_b128 v[112:115], v67 offset:0
	ds_read_b128 v[116:119], v67 offset:2048
	ds_read_b128 v[76:79], v65 offset:0
	v_mfma_f32_16x16x32_bf16 v[36:39], v[176:179], v[200:203], v[36:39]
	ds_read_b128 v[80:83], v65 offset:2048
	ds_read_b128 v[84:87], v65 offset:4096
	ds_read_b128 v[88:91], v65 offset:6144
	s_waitcnt lgkmcnt(0)
	s_barrier
	v_mfma_f32_16x16x32_bf16 v[60:63], v[220:223], v[236:239], v[60:63]
	v_mfma_f32_16x16x32_bf16 v[68:71], v[220:223], v[240:243], v[68:71]
	v_mfma_f32_16x16x32_bf16 v[52:55], v[220:223], v[244:247], v[52:55]
	v_mfma_f32_16x16x32_bf16 v[40:43], v[220:223], v[248:251], v[40:43]
	v_mfma_f32_16x16x32_bf16 v[72:75], v[224:227], v[236:239], v[72:75]
	v_mfma_f32_16x16x32_bf16 v[48:51], v[224:227], v[240:243], v[48:51]
	v_mfma_f32_16x16x32_bf16 v[44:47], v[224:227], v[244:247], v[44:47]
	v_mfma_f32_16x16x32_bf16 v[36:39], v[224:227], v[248:251], v[36:39]
	v_mfma_f32_16x16x32_bf16 v[60:63], v[112:115], v[76:79], v[60:63]
	v_mfma_f32_16x16x32_bf16 v[68:71], v[112:115], v[80:83], v[68:71]
	v_mfma_f32_16x16x32_bf16 v[52:55], v[112:115], v[84:87], v[52:55]
	v_mfma_f32_16x16x32_bf16 v[40:43], v[112:115], v[88:91], v[40:43]
	v_mfma_f32_16x16x32_bf16 v[72:75], v[116:119], v[76:79], v[72:75]
	v_mfma_f32_16x16x32_bf16 v[48:51], v[116:119], v[80:83], v[48:51]
	v_mfma_f32_16x16x32_bf16 v[44:47], v[116:119], v[84:87], v[44:47]
	v_mfma_f32_16x16x32_bf16 v[36:39], v[116:119], v[88:91], v[36:39]
